# 136 sample-attention workgroups (17 per XCD) and 120 compute workgroups (15 per XCD) with the per-XCD flash queues
# speedup vs baseline: 1.0079x; 1.0079x over previous
.LBB0_1582:
	v_readlane_b32 s0, v255, 12
	v_readlane_b32 s1, v255, 13
	s_cmp_lt_i32 s0, 7
	s_cselect_b64 s[0:1], -1, 0
	s_and_b64 s[18:19], s[0:1], s[2:3]
	s_andn2_b64 vcc, exec, s[18:19]
	s_cbranch_vccnz .LBB0_2069
	s_and_b32 s37, s87, 0xffffffc0
	s_waitcnt vmcnt(0)
	v_mbcnt_lo_u32_b32 v0, -1, 0
	v_mbcnt_hi_u32_b32 v0, -1, v0
	s_mov_b32 s22, 0
	v_add_u32_e32 v0, s37, v0
	s_ashr_i32 s23, s22, 31
	v_readlane_b32 s0, v255, 4
	v_readlane_b32 s1, v255, 5
	s_add_u32 s20, s0, s22
	s_addc_u32 s21, s1, s23
	s_sub_i32 s0, s73, 0x88
	s_cmp_lt_i32 s33, s0
	v_readlane_b32 s0, v255, 9
	v_readlane_b32 s1, v255, 10
	s_mov_b32 s1, 0
	v_writelane_b32 v255, s0, 9
	s_nop 1
	v_writelane_b32 v255, s1, 10
	s_cbranch_scc1 .LBB0_1624
	v_mbcnt_lo_u32_b32 v0, -1, 0
	v_mbcnt_hi_u32_b32 v0, -1, v0
	v_readlane_b32 s0, v255, 14
	v_add_u32_e32 v0, s37, v0
	s_cmp_lt_u32 s0, 64
	v_readlane_b32 s30, v255, 9
	s_cselect_b64 s[0:1], -1, 0
	s_add_i32 s2, s30, 1
	v_and_b32_e32 v176, 63, v0
	v_cvt_f32_u32_e32 v0, s2
	s_mov_b32 s3, 0x42fc0000
	v_mov_b32_e32 v1, 0x42800000
	s_lshl_b32 s2, s30, 14
	v_cmp_lt_f32_e32 vcc, s3, v0
	s_add_i32 s39, s2, 0
	s_and_b64 s[2:3], vcc, exec
	v_cndmask_b32_e32 v1, 0, v1, vcc
	v_sub_f32_e32 v0, v1, v0
	v_exp_f32_e32 v0, v0
	s_cselect_b32 s2, 0xffffffc0, 0
	v_readlane_b32 s31, v255, 10
	v_readlane_b32 s6, v255, 2
	v_ldexp_f32 v0, v0, s2
	s_lshl_b32 s2, s30, 8
	s_add_u32 s4, s20, s2
	s_addc_u32 s5, s21, 0
	s_add_u32 s8, s4, 0x47000000
	s_addc_u32 s9, s5, 0
	s_lshl_b64 s[10:11], s[30:31], 7
	s_lshl_b64 s[2:3], s[22:23], 3
	v_readlane_b32 s7, v255, 3
	s_add_u32 s12, s6, s2
	s_addc_u32 s13, s7, s3
	s_add_u32 s14, s20, 0x61800000
	s_addc_u32 s15, s21, 0
	s_add_u32 s16, s20, 0x61900000
	s_addc_u32 s17, s21, 0
	s_add_u32 s24, s20, 0x61a00000
	s_addc_u32 s25, s21, 0
	s_add_u32 s26, s4, 0x48100000
	s_addc_u32 s27, s5, 0
	s_add_u32 s28, s4, 0x49200000
	v_mul_f32_e32 v177, 0x3fb8aa3b, v0
	s_addc_u32 s29, s5, 0
	v_cndmask_b32_e64 v0, 0, 1, s[0:1]
	s_add_i32 s46, 0, 0x23f40
	s_movk_i32 s44, 0x2000
	s_add_i32 s45, s39, 0x2000
	s_lshl_b64 s[30:31], s[30:31], 9
	v_cmp_ne_u32_e64 s[2:3], 1, v0
	v_mov_b32_e32 v137, 0
	v_mov_b32_e32 v178, s46
	s_movk_i32 s47, 0x110
	s_movk_i32 s49, 0x4000
	s_movk_i32 s56, 0x6000
	s_mov_b32 s57, 0x8000
	s_mov_b32 s58, 0xa000
	s_mov_b32 s59, 0xc000
	s_mov_b32 s60, 0xe000
	s_mov_b32 s61, 0x10000
	s_mov_b32 s62, 0x12000
	s_mov_b32 s63, 0x14000
	s_mov_b32 s64, 0x16000
	s_mov_b32 s65, 0x18000
	s_mov_b32 s66, 0x1a000
	s_mov_b32 s67, 0x1c000
	s_mov_b32 s68, 0x1e000
	s_mov_b32 s69, 0x64000
	s_mov_b32 s70, 0x66000
	s_mov_b32 s71, 0x68000
	s_mov_b32 s72, 0x6a000
	s_mov_b32 s74, 0x6c000
	s_mov_b32 s76, 0x6e000
	s_mov_b32 s77, 0x70000
	s_mov_b32 s78, 0x72000
	s_mov_b32 s79, 0x74000
	s_mov_b32 s80, 0x76000
	s_mov_b32 s81, 0x78000
	s_mov_b32 s82, 0x7a000
	s_mov_b32 s83, 0x7c000
	s_mov_b32 s84, 0x7e000
	s_movk_i32 s85, 0x210
	s_movk_i32 s86, 0x1000
	s_mov_b32 s87, 0x61a00000
	v_mov_b32_e32 v179, 0xf149f2ca
	s_mov_b32 s96, 0
	s_branch .LBB0_1588
